# GEMM tile head: 80 of 128 accumulator VGPRs zeroed by 5 bf16 MFMAs (0*0+0) on the idle matrix pipe, interleaved with VALU moves
# baseline (speedup 1.0000x reference)
.LBB0_56:
	s_ashr_i32 s37, s36, 31
	v_cmp_lt_i64_e32 vcc, s[40:41], v[150:151]
	s_lshl_b64 s[40:41], s[36:37], 19
	s_add_u32 s40, s52, s40
	s_addc_u32 s41, s53, s41
	s_and_b64 s[44:45], vcc, exec
	s_cselect_b32 s37, s41, s1
	s_cselect_b32 s60, s40, s0
	s_ashr_i32 s35, s34, 31
	s_lshl_b64 s[44:45], s[34:35], 19
	s_add_u32 s44, s19, s44
	s_addc_u32 s45, s24, s45
	s_and_b64 s[48:49], vcc, exec
	s_cselect_b32 s35, s45, s23
	s_cselect_b32 s61, s44, s22
	s_add_u32 s0, s0, 0x40080
	s_addc_u32 s1, s1, 0
	s_add_u32 s62, s22, 0x100
	s_addc_u32 s63, s23, 0
	s_mov_b32 s64, -2
	v_mov_b64_e32 v[82:83], 0
	v_mov_b64_e32 v[84:85], 0
	s_nop 1
	v_mfma_f32_32x32x16_bf16 v[2:17], v[82:85], v[82:85], 0
	v_mov_b64_e32 v[114:115], 0
	v_mov_b64_e32 v[116:117], 0
	v_mov_b64_e32 v[118:119], 0
	v_mov_b64_e32 v[120:121], 0
	v_mov_b64_e32 v[122:123], 0
	v_mfma_f32_32x32x16_bf16 v[18:33], v[82:85], v[82:85], 0
	v_mov_b64_e32 v[124:125], 0
	v_mov_b64_e32 v[126:127], 0
	v_mov_b64_e32 v[128:129], 0
	v_mov_b64_e32 v[98:99], 0
	v_mov_b64_e32 v[100:101], 0
	v_mfma_f32_32x32x16_bf16 v[34:49], v[82:85], v[82:85], 0
	v_mov_b64_e32 v[102:103], 0
	v_mov_b64_e32 v[104:105], 0
	v_mov_b64_e32 v[106:107], 0
	v_mov_b64_e32 v[108:109], 0
	v_mov_b64_e32 v[110:111], 0
	v_mfma_f32_32x32x16_bf16 v[50:65], v[82:85], v[82:85], 0
	v_mov_b64_e32 v[112:113], 0
	v_mov_b64_e32 v[86:87], 0
	v_mov_b64_e32 v[88:89], 0
	v_mov_b64_e32 v[90:91], 0
	v_mov_b64_e32 v[92:93], 0
	v_mfma_f32_32x32x16_bf16 v[66:81], v[82:85], v[82:85], 0
	v_mov_b64_e32 v[94:95], 0
	v_mov_b64_e32 v[96:97], 0

.LBB0_94:
	s_ashr_i32 s49, s48, 31
	s_lshl_b64 s[26:27], s[48:49], 19
	s_add_u32 s50, s14, s26
	v_cmp_lt_i64_e32 vcc, s[28:29], v[152:153]
	s_addc_u32 s51, s15, s27
	s_and_b64 s[26:27], vcc, exec
	s_cselect_b32 s25, s51, s9
	s_cselect_b32 s26, s50, s8
	s_ashr_i32 s47, s46, 31
	s_lshl_b64 s[28:29], s[46:47], 19
	s_add_u32 s54, s19, s28
	s_addc_u32 s55, s34, s29
	s_and_b64 s[28:29], vcc, exec
	s_cselect_b32 s27, s55, s23
	s_cselect_b32 s30, s54, s22
	s_add_u32 s8, s8, 0x40080
	s_addc_u32 s9, s9, 0
	s_add_u32 s31, s22, 0x100
	s_addc_u32 s47, s23, 0
	s_mov_b32 s49, -2
	v_mov_b64_e32 v[50:51], 0
	v_mov_b64_e32 v[52:53], 0
	s_nop 1
	v_mfma_f32_32x32x16_bf16 v[2:17], v[50:53], v[50:53], 0
	v_mov_b64_e32 v[54:55], 0
	v_mov_b64_e32 v[56:57], 0
	v_mov_b64_e32 v[62:63], 0
	v_mov_b64_e32 v[64:65], 0
	v_mov_b64_e32 v[70:71], 0
	v_mfma_f32_32x32x16_bf16 v[18:33], v[50:53], v[50:53], 0
	v_mov_b64_e32 v[72:73], 0
	v_mov_b64_e32 v[130:131], 0
	v_mov_b64_e32 v[132:133], 0
	v_mov_b64_e32 v[134:135], 0
	v_mov_b64_e32 v[136:137], 0
	v_mfma_f32_32x32x16_bf16 v[34:49], v[50:53], v[50:53], 0
	v_mov_b64_e32 v[138:139], 0
	v_mov_b64_e32 v[140:141], 0
	v_mov_b64_e32 v[142:143], 0
	v_mov_b64_e32 v[144:145], 0
	v_mov_b64_e32 v[114:115], 0
	v_mfma_f32_32x32x16_bf16 v[82:97], v[50:53], v[50:53], 0
	v_mov_b64_e32 v[116:117], 0
	v_mov_b64_e32 v[118:119], 0
	v_mov_b64_e32 v[120:121], 0
	v_mov_b64_e32 v[122:123], 0
	v_mov_b64_e32 v[124:125], 0
	v_mfma_f32_32x32x16_bf16 v[98:113], v[50:53], v[50:53], 0
	v_mov_b64_e32 v[126:127], 0
	v_mov_b64_e32 v[128:129], 0

.LBB0_259:
	s_ashr_i32 s35, s34, 31
	v_cmp_lt_i64_e32 vcc, s[36:37], v[150:151]
	s_lshl_b64 s[36:37], s[34:35], 19
	s_add_u32 s36, s12, s36
	s_addc_u32 s37, s13, s37
	s_and_b64 s[42:43], vcc, exec
	s_cselect_b32 s35, s37, s1
	s_cselect_b32 s55, s36, s0
	s_ashr_i32 s31, s30, 31
	s_lshl_b64 s[42:43], s[30:31], 19
	s_add_u32 s42, s17, s42
	s_addc_u32 s43, s19, s43
	s_and_b64 s[46:47], vcc, exec
	s_cselect_b32 s31, s43, s23
	s_cselect_b32 s56, s42, s22
	s_add_u32 s0, s0, 0x40080
	s_addc_u32 s1, s1, 0
	s_add_u32 s57, s22, 0x100
	s_addc_u32 s58, s23, 0
	s_mov_b32 s59, -2
	v_mov_b64_e32 v[82:83], 0
	v_mov_b64_e32 v[84:85], 0
	s_nop 1
	v_mfma_f32_32x32x16_bf16 v[2:17], v[82:85], v[82:85], 0
	v_mov_b64_e32 v[114:115], 0
	v_mov_b64_e32 v[116:117], 0
	v_mov_b64_e32 v[118:119], 0
	v_mov_b64_e32 v[120:121], 0
	v_mov_b64_e32 v[122:123], 0
	v_mfma_f32_32x32x16_bf16 v[18:33], v[82:85], v[82:85], 0
	v_mov_b64_e32 v[124:125], 0
	v_mov_b64_e32 v[126:127], 0
	v_mov_b64_e32 v[128:129], 0
	v_mov_b64_e32 v[98:99], 0
	v_mov_b64_e32 v[100:101], 0
	v_mfma_f32_32x32x16_bf16 v[34:49], v[82:85], v[82:85], 0
	v_mov_b64_e32 v[102:103], 0
	v_mov_b64_e32 v[104:105], 0
	v_mov_b64_e32 v[106:107], 0
	v_mov_b64_e32 v[108:109], 0
	v_mov_b64_e32 v[110:111], 0
	v_mfma_f32_32x32x16_bf16 v[50:65], v[82:85], v[82:85], 0
	v_mov_b64_e32 v[112:113], 0
	v_mov_b64_e32 v[86:87], 0
	v_mov_b64_e32 v[88:89], 0
	v_mov_b64_e32 v[90:91], 0
	v_mov_b64_e32 v[92:93], 0
	v_mfma_f32_32x32x16_bf16 v[66:81], v[82:85], v[82:85], 0
	v_mov_b64_e32 v[94:95], 0
	v_mov_b64_e32 v[96:97], 0

.LBB0_330:
	s_add_u32 s40, s22, 0x100
	s_addc_u32 s41, s23, 0
	s_mov_b32 s51, -2
	v_mov_b64_e32 v[82:83], 0
	v_mov_b64_e32 v[84:85], 0
	s_nop 1
	v_mfma_f32_32x32x16_bf16 v[2:17], v[82:85], v[82:85], 0
	v_mov_b64_e32 v[114:115], 0
	v_mov_b64_e32 v[116:117], 0
	v_mov_b64_e32 v[118:119], 0
	v_mov_b64_e32 v[120:121], 0
	v_mov_b64_e32 v[122:123], 0
	v_mfma_f32_32x32x16_bf16 v[18:33], v[82:85], v[82:85], 0
	v_mov_b64_e32 v[124:125], 0
	v_mov_b64_e32 v[126:127], 0
	v_mov_b64_e32 v[128:129], 0
	v_mov_b64_e32 v[98:99], 0
	v_mov_b64_e32 v[100:101], 0
	v_mfma_f32_32x32x16_bf16 v[34:49], v[82:85], v[82:85], 0
	v_mov_b64_e32 v[102:103], 0
	v_mov_b64_e32 v[104:105], 0
	v_mov_b64_e32 v[106:107], 0
	v_mov_b64_e32 v[108:109], 0
	v_mov_b64_e32 v[110:111], 0
	v_mfma_f32_32x32x16_bf16 v[50:65], v[82:85], v[82:85], 0
	v_mov_b64_e32 v[112:113], 0
	v_mov_b64_e32 v[86:87], 0
	v_mov_b64_e32 v[88:89], 0
	v_mov_b64_e32 v[90:91], 0
	v_mov_b64_e32 v[92:93], 0
	v_mfma_f32_32x32x16_bf16 v[66:81], v[82:85], v[82:85], 0
	v_mov_b64_e32 v[94:95], 0
	v_mov_b64_e32 v[96:97], 0

.LBB0_359:
	s_ashr_i32 s35, s34, 31
	v_cmp_lt_i64_e32 vcc, s[36:37], v[156:157]
	s_lshl_b64 s[36:37], s[34:35], 19
	s_add_u32 s36, s12, s36
	s_addc_u32 s37, s13, s37
	s_and_b64 s[40:41], vcc, exec
	s_cselect_b32 s1, s37, s45
	s_cselect_b32 s3, s36, s44
	s_ashr_i32 s31, s30, 31
	s_lshl_b64 s[40:41], s[30:31], 19
	s_add_u32 s40, s48, s40
	s_addc_u32 s41, s49, s41
	s_and_b64 s[46:47], vcc, exec
	s_cselect_b32 s31, s41, s43
	s_cselect_b32 s35, s40, s42
	s_add_u32 s60, s42, 0x100
	s_addc_u32 s61, s43, 0
	s_add_u32 s42, s44, 0x40080
	s_addc_u32 s43, s45, 0
	s_mov_b32 s62, -2
	v_mov_b64_e32 v[98:99], 0
	v_mov_b64_e32 v[100:101], 0
	s_nop 1
	v_mfma_f32_32x32x16_bf16 v[2:17], v[98:101], v[98:101], 0
	v_mov_b64_e32 v[130:131], 0
	v_mov_b64_e32 v[132:133], 0
	v_mov_b64_e32 v[134:135], 0
	v_mov_b64_e32 v[136:137], 0
	v_mov_b64_e32 v[138:139], 0
	v_mfma_f32_32x32x16_bf16 v[18:33], v[98:101], v[98:101], 0
	v_mov_b64_e32 v[140:141], 0
	v_mov_b64_e32 v[142:143], 0
	v_mov_b64_e32 v[144:145], 0
	v_mov_b64_e32 v[114:115], 0
	v_mov_b64_e32 v[116:117], 0
	v_mfma_f32_32x32x16_bf16 v[34:49], v[98:101], v[98:101], 0
	v_mov_b64_e32 v[118:119], 0
	v_mov_b64_e32 v[120:121], 0
	v_mov_b64_e32 v[122:123], 0
	v_mov_b64_e32 v[124:125], 0
	v_mov_b64_e32 v[126:127], 0
	v_mfma_f32_32x32x16_bf16 v[50:65], v[98:101], v[98:101], 0
	v_mov_b64_e32 v[128:129], 0
	v_mov_b64_e32 v[102:103], 0
	v_mov_b64_e32 v[104:105], 0
	v_mov_b64_e32 v[106:107], 0
	v_mov_b64_e32 v[108:109], 0
	v_mfma_f32_32x32x16_bf16 v[66:81], v[98:101], v[98:101], 0
	v_mov_b64_e32 v[110:111], 0
	v_mov_b64_e32 v[112:113], 0

.LBB0_585:
	s_ashr_i32 s9, s8, 31
	v_cmp_lt_i64_e32 vcc, s[16:17], v[160:161]
	s_lshl_b64 s[16:17], s[8:9], 19
	s_add_u32 s16, s12, s16
	s_addc_u32 s17, s13, s17
	s_and_b64 s[18:19], vcc, exec
	s_cselect_b32 s9, s17, s21
	s_cselect_b32 s43, s16, s20
	s_ashr_i32 s1, s0, 31
	s_lshl_b64 s[18:19], s[0:1], 19
	s_add_u32 s18, s27, s18
	s_addc_u32 s19, s28, s19
	s_and_b64 s[24:25], vcc, exec
	s_cselect_b32 s1, s19, s23
	s_cselect_b32 s44, s18, s22
	s_add_u32 s20, s20, 0x40080
	s_addc_u32 s21, s21, 0
	s_add_u32 s45, s22, 0x100
	s_addc_u32 s46, s23, 0
	s_mov_b32 s47, -2
	v_mov_b64_e32 v[82:83], 0
	v_mov_b64_e32 v[84:85], 0
	s_nop 1
	v_mfma_f32_32x32x16_bf16 v[2:17], v[82:85], v[82:85], 0
	v_mov_b64_e32 v[114:115], 0
	v_mov_b64_e32 v[116:117], 0
	v_mov_b64_e32 v[118:119], 0
	v_mov_b64_e32 v[120:121], 0
	v_mov_b64_e32 v[122:123], 0
	v_mfma_f32_32x32x16_bf16 v[18:33], v[82:85], v[82:85], 0
	v_mov_b64_e32 v[124:125], 0
	v_mov_b64_e32 v[126:127], 0
	v_mov_b64_e32 v[128:129], 0
	v_mov_b64_e32 v[98:99], 0
	v_mov_b64_e32 v[100:101], 0
	v_mfma_f32_32x32x16_bf16 v[34:49], v[82:85], v[82:85], 0
	v_mov_b64_e32 v[102:103], 0
	v_mov_b64_e32 v[104:105], 0
	v_mov_b64_e32 v[106:107], 0
	v_mov_b64_e32 v[108:109], 0
	v_mov_b64_e32 v[110:111], 0
	v_mfma_f32_32x32x16_bf16 v[50:65], v[82:85], v[82:85], 0
	v_mov_b64_e32 v[112:113], 0
	v_mov_b64_e32 v[86:87], 0
	v_mov_b64_e32 v[88:89], 0
	v_mov_b64_e32 v[90:91], 0
	v_mov_b64_e32 v[92:93], 0
	v_mfma_f32_32x32x16_bf16 v[66:81], v[82:85], v[82:85], 0
	v_mov_b64_e32 v[94:95], 0
	v_mov_b64_e32 v[96:97], 0
